# window LDS ring carried across token iterations: each window step requests stream position p+2 incl. the next token's first two tiles; no start-of-window barrier or exposed DMA round trip
# speedup vs baseline: 1.0227x; 1.0019x over previous
.LBB0_419:
	s_and_saveexec_b64 s[78:79], s[4:5]
	s_cbranch_execz .LBB0_418
	s_lshl_b32 s0, s74, 2
	v_and_or_b32 v1, s0, 12, v209
	s_lshl_b32 s0, s74, 12
	s_mov_b32 s75, s73
	s_and_b32 s92, s0, 0x4000
	s_lshl_b64 s[0:1], s[74:75], 17
	v_lshl_add_u64 v[172:173], v[162:163], 0, s[0:1]
	s_mov_b64 s[12:13], 0x1000
	v_lshl_add_u64 v[174:175], v[172:173], 0, s[12:13]
	s_mov_b64 s[12:13], 0x1400
	v_lshl_add_u64 v[176:177], v[172:173], 0, s[12:13]
	s_mov_b64 s[12:13], 0x1800
	v_lshl_add_u64 v[178:179], v[172:173], 0, s[12:13]
	s_mov_b64 s[12:13], 0x1c00
	v_lshl_add_u64 v[182:183], v[164:165], 0, s[0:1]
	s_lshl_b64 s[0:1], s[74:75], 20
	v_lshl_add_u64 v[180:181], v[172:173], 0, s[12:13]
	s_add_u32 s12, s46, s0
	v_lshlrev_b32_e32 v2, 7, v1
	v_mov_b32_e32 v3, v0
	v_cmp_lt_i32_e32 vcc, v197, v195
	s_addc_u32 s13, s47, s1
	v_lshl_add_u64 v[170:171], v[156:157], 0, v[2:3]
	v_cndmask_b32_e32 v2, v193, v197, vcc
	v_cmp_lt_i32_e32 vcc, v206, v195
	s_add_u32 s0, s42, s0
	v_lshlrev_b32_e32 v223, 2, v2
	v_cndmask_b32_e32 v2, v193, v206, vcc
	s_addc_u32 s1, s43, s1
	s_lshl_b64 s[14:15], s[74:75], 21
	v_lshl_or_b32 v190, v1, 6, v212
	v_lshlrev_b32_e32 v224, 2, v2
	v_mul_u32_u24_e32 v184, 3, v1
	v_mov_b32_e32 v185, v0
	v_lshl_add_u64 v[186:187], v[166:167], 0, s[14:15]
	v_lshl_add_u64 v[188:189], v[168:169], 0, s[14:15]
	v_or_b32_e32 v192, 16, v190
	v_or_b32_e32 v194, 32, v190
	v_or_b32_e32 v196, 48, v190
	v_lshl_add_u64 v[198:199], s[0:1], 0, v[160:161]
	v_lshl_add_u64 v[200:201], s[12:13], 0, v[160:161]
	s_mov_b64 s[80:81], 0
	v_mov_b32_e32 v225, v219
	v_mov_b32_e32 v226, v211
	v_readfirstlane_b32 s75, v191
	v_lshlrev_b32_e32 v237, 2, v226
	s_mov_b32 s95, 0
	s_lshl_b32 s75, s75, 4
	v_readfirstlane_b32 s98, v237
	s_mov_b32 s94, s75
	v_lshl_add_u64 v[64:65], v[186:187], 0, s[94:95]
	v_lshl_add_u64 v[66:67], v[188:189], 0, s[94:95]
	v_add_u32_e32 v237, s55, v226
	v_lshlrev_b32_e32 v237, 2, v237
	s_mov_b32 s36, 0x10010
	s_mov_b32 s37, 0x14010
	s_mov_b32 s72, 0x18010
	v_readfirstlane_b32 s101, v237
	s_and_b32 s93, s98, 0xffffffe0
	s_max_i32 s12, s93, 0x1ff
	s_sub_i32 s12, s12, 0x1ff
	s_lshr_b32 s12, s12, 6
	s_add_i32 s13, s93, 31
	s_lshr_b32 s13, s13, 6
	s_and_b32 s93, s101, 0xffffffe0
	s_max_i32 s100, s93, 0x1ff
	s_sub_i32 s100, s100, 0x1ff
	s_lshr_b32 s100, s100, 6
	s_add_i32 s99, s12, 1
	s_cmp_le_i32 s99, s13
	s_cselect_b32 s99, s99, s100
	v_writelane_b32 v254, s36, 0
	v_writelane_b32 v254, s37, 1
	v_writelane_b32 v254, s72, 2
	s_barrier
	s_lshl_b32 s94, s12, 13
	s_add_i32 m0, s36, s75
	v_lshl_add_u64 v[62:63], v[64:65], 0, s[94:95]
	s_add_i32 s93, s36, 0x2000
	global_load_lds_dwordx4 v[62:63], off
	v_lshl_add_u64 v[62:63], v[66:67], 0, s[94:95]
	s_add_i32 m0, s93, s75
	s_nop 0
	global_load_lds_dwordx4 v[62:63], off
	s_lshl_b32 s94, s99, 13
	s_add_i32 m0, s37, s75
	v_lshl_add_u64 v[62:63], v[64:65], 0, s[94:95]
	s_add_i32 s93, s37, 0x2000
	global_load_lds_dwordx4 v[62:63], off
	v_lshl_add_u64 v[62:63], v[66:67], 0, s[94:95]
	s_add_i32 m0, s93, s75
	s_nop 0
	global_load_lds_dwordx4 v[62:63], off
	s_branch .LBB0_423

.LBB0_422:
	s_or_b64 exec, exec, s[14:15]
	v_or_b32_e32 v134, v202, v190
	v_mov_b32_e32 v135, v203
	v_lshl_add_u64 v[142:143], v[204:205], 2, s[58:59]
	v_lshlrev_b64 v[134:135], 1, v[134:135]
	global_load_dword v132, v[142:143], off
	v_lshl_add_u64 v[134:135], s[62:63], 0, v[134:135]
	v_or_b32_e32 v136, v202, v192
	v_mov_b32_e32 v137, v203
	global_load_dwordx2 v[124:125], v[134:135], off
	v_lshlrev_b64 v[136:137], 1, v[136:137]
	v_or_b32_e32 v138, v202, v194
	v_mov_b32_e32 v139, v203
	v_lshl_add_u64 v[136:137], s[62:63], 0, v[136:137]
	v_lshlrev_b64 v[138:139], 1, v[138:139]
	global_load_dwordx2 v[126:127], v[136:137], off
	v_lshl_add_u64 v[138:139], s[62:63], 0, v[138:139]
	v_or_b32_e32 v140, v202, v196
	v_mov_b32_e32 v141, v203
	global_load_dwordx2 v[128:129], v[138:139], off
	v_lshlrev_b64 v[140:141], 1, v[140:141]
	v_lshl_add_u64 v[140:141], s[62:63], 0, v[140:141]
	global_load_dwordx2 v[130:131], v[140:141], off
	v_or_b32_e32 v30, v202, v190
	v_mov_b32_e32 v31, v203
	v_lshlrev_b64 v[30:31], 1, v[30:31]
	ds_read2st64_b32 v[2:3], v213 offset1:1
	ds_read2st64_b32 v[12:13], v213 offset0:2 offset1:3
	ds_read2st64_b32 v[14:15], v213 offset0:4 offset1:5
	ds_read2st64_b32 v[16:17], v213 offset0:6 offset1:7
	ds_read2st64_b32 v[18:19], v213 offset0:8 offset1:9
	ds_read2st64_b32 v[24:25], v213 offset0:10 offset1:11
	ds_read2st64_b32 v[26:27], v213 offset0:12 offset1:13
	ds_read2st64_b32 v[28:29], v213 offset0:14 offset1:15
	ds_bpermute_b32 v34, v223, v234
	v_mov_b32_e32 v35, v203
	v_lshl_add_u64 v[30:31], s[48:49], 0, v[30:31]
	v_add_u32_e32 v226, s55, v226
	v_add_u32_e32 v225, s77, v225
	s_waitcnt lgkmcnt(0)
	v_add_f32_e32 v36, v234, v34
	ds_bpermute_b32 v37, v224, v36
	v_or_b32_e32 v34, v202, v192
	v_lshlrev_b64 v[34:35], 1, v[34:35]
	s_waitcnt lgkmcnt(0)
	v_add_f32_e32 v38, v36, v37
	v_div_scale_f32 v39, s[0:1], v38, v38, 1.0
	v_rcp_f32_e32 v40, v39
	v_div_scale_f32 v41, vcc, 1.0, v38, 1.0
	v_fma_f32 v42, -v39, v40, 1.0
	v_fmac_f32_e32 v40, v42, v40
	v_mul_f32_e32 v42, v41, v40
	v_fma_f32 v43, -v39, v42, v41
	v_fmac_f32_e32 v42, v43, v40
	v_fma_f32 v39, -v39, v42, v41
	v_div_fmas_f32 v39, v39, v40, v42
	v_div_fixup_f32 v39, v39, v38, 1.0
	v_cmp_lt_f32_e32 vcc, 0, v38
	s_waitcnt vmcnt(0)
	v_mov_b32_e32 v1, v132
	v_mov_b64_e32 v[32:33], v[124:125]
	v_lshlrev_b32_e32 v40, 16, v32
	v_cndmask_b32_e32 v38, 0, v39, vcc
	v_mul_f32_e32 v38, v1, v38
	v_pk_fma_f32 v[2:3], v[38:39], v[44:45], v[2:3] op_sel_hi:[0,1,1]
	v_pk_fma_f32 v[12:13], v[38:39], v[46:47], v[12:13] op_sel_hi:[0,1,1]
	v_and_b32_e32 v41, 0xffff0000, v32
	v_lshlrev_b32_e32 v32, 16, v33
	v_and_b32_e32 v33, 0xffff0000, v33
	v_pk_mul_f32 v[2:3], v[2:3], v[40:41]
	v_pk_mul_f32 v[12:13], v[12:13], v[32:33]
	v_cvt_pk_bf16_f32 v2, v2, v3
	v_cvt_pk_bf16_f32 v3, v12, v13
	global_store_dwordx2 v[30:31], v[2:3], off
	v_pk_fma_f32 v[14:15], v[38:39], v[20:21], v[14:15] op_sel_hi:[0,1,1]
	v_pk_fma_f32 v[16:17], v[38:39], v[22:23], v[16:17] op_sel_hi:[0,1,1]
	v_or_b32_e32 v12, v202, v194
	v_mov_b32_e32 v13, v203
	v_lshlrev_b64 v[12:13], 1, v[12:13]
	v_lshl_add_u64 v[30:31], s[48:49], 0, v[34:35]
	v_pk_fma_f32 v[4:5], v[38:39], v[4:5], v[18:19] op_sel_hi:[0,1,1]
	v_pk_fma_f32 v[6:7], v[38:39], v[6:7], v[24:25] op_sel_hi:[0,1,1]
	v_or_b32_e32 v202, v202, v196
	v_lshl_add_u64 v[12:13], s[48:49], 0, v[12:13]
	v_cmp_lt_i32_e32 vcc, s91, v226
	s_or_b64 s[80:81], vcc, s[80:81]
	v_mov_b64_e32 v[2:3], v[126:127]
	v_lshlrev_b32_e32 v20, 16, v2
	v_and_b32_e32 v21, 0xffff0000, v2
	v_lshlrev_b32_e32 v2, 16, v3
	v_and_b32_e32 v3, 0xffff0000, v3
	v_pk_mul_f32 v[14:15], v[14:15], v[20:21]
	v_pk_mul_f32 v[2:3], v[16:17], v[2:3]
	v_cvt_pk_bf16_f32 v14, v14, v15
	v_cvt_pk_bf16_f32 v15, v2, v3
	global_store_dwordx2 v[30:31], v[14:15], off
	v_lshlrev_b64 v[14:15], 1, v[202:203]
	v_mov_b64_e32 v[2:3], v[128:129]
	v_lshlrev_b32_e32 v18, 16, v2
	v_and_b32_e32 v19, 0xffff0000, v2
	v_lshlrev_b32_e32 v2, 16, v3
	v_and_b32_e32 v3, 0xffff0000, v3
	v_pk_mul_f32 v[4:5], v[4:5], v[18:19]
	v_pk_mul_f32 v[2:3], v[6:7], v[2:3]
	v_cvt_pk_bf16_f32 v4, v4, v5
	v_cvt_pk_bf16_f32 v5, v2, v3
	global_store_dwordx2 v[12:13], v[4:5], off
	v_pk_fma_f32 v[6:7], v[38:39], v[8:9], v[26:27] op_sel_hi:[0,1,1]
	v_pk_fma_f32 v[8:9], v[38:39], v[10:11], v[28:29] op_sel_hi:[0,1,1]
	v_lshl_add_u64 v[4:5], s[48:49], 0, v[14:15]
	v_mov_b64_e32 v[2:3], v[130:131]
	v_lshlrev_b32_e32 v10, 16, v2
	v_and_b32_e32 v11, 0xffff0000, v2
	v_lshlrev_b32_e32 v2, 16, v3
	v_and_b32_e32 v3, 0xffff0000, v3
	v_pk_mul_f32 v[6:7], v[6:7], v[10:11]
	v_pk_mul_f32 v[2:3], v[8:9], v[2:3]
	v_cvt_pk_bf16_f32 v6, v6, v7
	v_cvt_pk_bf16_f32 v7, v2, v3
	global_store_dwordx2 v[4:5], v[6:7], off
	s_andn2_b64 exec, exec, s[80:81]
	s_cbranch_execz .LBB0_418

.LBB0_607:
	s_or_b64 exec, exec, s[16:17]
	v_lshl_add_u64 v[2:3], v[204:205], 2, s[52:53]
	global_load_dword v56, v[2:3], off
	global_load_dwordx4 v[12:15], v[148:149], off offset:64
	global_load_dwordx4 v[16:19], v[148:149], off
	ds_bpermute_b32 v4, v223, v237
	ds_read2st64_b32 v[8:9], v213 offset1:1
	ds_read2st64_b32 v[10:11], v213 offset0:2 offset1:3
	ds_read2st64_b32 v[54:55], v213 offset0:4 offset1:5
	ds_read_b32 v57, v213 offset:1536
	v_max_i32_e32 v5, 0x1ff, v227
	v_mov_b32_e32 v2, v0
	v_mov_b32_e32 v3, v0
	s_waitcnt lgkmcnt(4)
	v_add_f32_e32 v58, v237, v4
	ds_bpermute_b32 v59, v224, v58
	v_add_u32_e32 v48, 0xfffffe01, v5
	v_mov_b32_e32 v1, v0
	v_mov_b64_e32 v[46:47], v[2:3]
	v_mov_b64_e32 v[22:23], v[2:3]
	s_waitcnt lgkmcnt(0)
	v_add_f32_e32 v58, v58, v59
	v_div_scale_f32 v59, s[0:1], v58, v58, 1.0
	v_rcp_f32_e32 v60, v59
	v_div_scale_f32 v61, vcc, 1.0, v58, 1.0
	v_mov_b64_e32 v[6:7], v[2:3]
	v_fma_f32 v62, -v59, v60, 1.0
	v_fmac_f32_e32 v60, v62, v60
	v_mul_f32_e32 v62, v61, v60
	v_fma_f32 v63, -v59, v62, v61
	v_fmac_f32_e32 v62, v63, v60
	v_fma_f32 v59, -v59, v62, v61
	v_div_fmas_f32 v59, v59, v60, v62
	v_div_fixup_f32 v59, v59, v58, 1.0
	v_cmp_lt_f32_e32 vcc, 0, v58
	v_lshrrev_b32_e32 v48, 6, v48
	v_mov_b32_e32 v234, 0
	v_cndmask_b32_e32 v58, 0, v59, vcc
	v_mov_b64_e32 v[44:45], v[0:1]
	v_mov_b64_e32 v[20:21], v[0:1]
	v_mov_b64_e32 v[4:5], v[0:1]
	v_cmp_le_i32_e64 s[0:1], v48, v229
	s_waitcnt vmcnt(2)
	v_mul_f32_e32 v56, v56, v58
	v_fma_f32 v8, v56, v40, v8
	v_fmac_f32_e32 v9, v56, v41
	v_fma_f32 v10, v56, v42, v10
	v_fmac_f32_e32 v11, v56, v43
	v_fma_f32 v36, v56, v36, v54
	v_fmac_f32_e32 v55, v56, v37
	v_fmac_f32_e32 v57, v56, v38
	v_fmac_f32_e32 v49, v56, v39
	v_fmac_f32_e32 v52, v56, v32
	v_fmac_f32_e32 v53, v56, v33
	v_fmac_f32_e32 v26, v56, v34
	v_fmac_f32_e32 v27, v56, v35
	v_fmac_f32_e32 v50, v56, v28
	v_fmac_f32_e32 v51, v56, v29
	v_fmac_f32_e32 v24, v56, v30
	v_fmac_f32_e32 v25, v56, v31
	ds_write2st64_b32 v213, v8, v9 offset1:1
	ds_write2st64_b32 v213, v10, v11 offset0:2 offset1:3
	ds_write2st64_b32 v213, v36, v55 offset0:4 offset1:5
	ds_write2st64_b32 v213, v57, v49 offset0:6 offset1:7
	ds_write2st64_b32 v213, v52, v53 offset0:8 offset1:9
	ds_write2st64_b32 v213, v26, v27 offset0:10 offset1:11
	ds_write2st64_b32 v213, v50, v51 offset0:12 offset1:13
	ds_write2st64_b32 v213, v24, v25 offset0:14 offset1:15
	v_mov_b64_e32 v[10:11], v[2:3]
	v_mov_b64_e32 v[8:9], v[0:1]
	s_waitcnt vmcnt(0)
	s_and_saveexec_b64 s[14:15], s[0:1]
	s_cbranch_execz .LBB0_422
	v_mov_b32_e32 v2, v0
	v_mov_b32_e32 v3, v0
	v_mov_b32_e32 v1, v0
	v_mov_b64_e32 v[46:47], v[2:3]
	v_mov_b64_e32 v[22:23], v[2:3]
	v_mov_b64_e32 v[6:7], v[2:3]
	v_mov_b64_e32 v[10:11], v[2:3]
	v_mov_b64_e32 v[44:45], v[0:1]
	v_mov_b64_e32 v[20:21], v[0:1]
	v_mov_b64_e32 v[4:5], v[0:1]
	v_mov_b64_e32 v[8:9], v[0:1]
	v_add_u32_e32 v231, 0xfffffe04, v227
	v_add_u32_e32 v232, 0xfffffe01, v228
	v_mov_b32_e32 v235, 0xf149f2ca
	v_mov_b32_e32 v236, 0
	v_readfirstlane_b32 s32, v227
	v_readfirstlane_b32 s22, v48
	v_readfirstlane_b32 s24, v229
	v_readfirstlane_b32 s75, v191
	v_and_b32_e32 v60, 63, v191
	v_lshlrev_b32_e32 v60, 4, v60
	s_mov_b32 s95, 0
	s_lshl_b32 s75, s75, 4
	s_and_b32 s93, s32, 0xffffffe0
	s_max_i32 s12, s93, 0x1ff
	s_sub_i32 s12, s12, 0x1ff
	s_lshr_b32 s12, s12, 6
	s_add_i32 s13, s93, 31
	s_lshr_b32 s13, s13, 6
	v_readlane_b32 s36, v254, 0
	v_readlane_b32 s37, v254, 1
	v_readlane_b32 s72, v254, 2
	s_mov_b32 s94, s75
	s_add_i32 s98, s32, 0xfffffe04
	v_lshl_add_u64 v[64:65], v[186:187], 0, s[94:95]
	v_lshl_add_u64 v[66:67], v[188:189], 0, s[94:95]
	v_add_u32_e32 v237, s55, v226
	v_lshlrev_b32_e32 v237, 2, v237
	s_nop 0
	v_readfirstlane_b32 s101, v237
	s_and_b32 s93, s101, 0xffffffe0
	s_max_i32 s100, s93, 0x1ff
	s_sub_i32 s100, s100, 0x1ff
	s_lshr_b32 s100, s100, 6
	s_sub_i32 s100, s100, s13
	s_add_i32 s100, s100, -1

.Lwin_bar:
	s_barrier
	s_add_i32 s99, s12, 2
	s_cmp_le_i32 s99, s13
	s_cselect_b32 s101, 0, s100
	s_add_i32 s99, s99, s101
	s_lshl_b32 s94, s99, 13
	s_add_i32 m0, s72, s75
	v_lshl_add_u64 v[62:63], v[64:65], 0, s[94:95]
	s_add_i32 s93, s72, 0x2000
	global_load_lds_dwordx4 v[62:63], off
	v_lshl_add_u64 v[62:63], v[66:67], 0, s[94:95]
	s_add_i32 m0, s93, s75
	s_nop 0
	global_load_lds_dwordx4 v[62:63], off

.Lwin_skip:
	s_mov_b32 s93, s36
	s_mov_b32 s36, s37
	s_mov_b32 s37, s72
	s_mov_b32 s72, s93
	s_add_i32 s12, s12, 1
	s_cmp_le_i32 s12, s13
	s_cbranch_scc1 .Lwin_loop
	v_writelane_b32 v254, s36, 0
	v_writelane_b32 v254, s37, 1
	v_writelane_b32 v254, s72, 2
	s_branch .LBB0_422
